# C2 row loop: row-invariant weights (gq half 1, gkv, gkr, conv half 0) resident in unused registers, conv half 1 in a per-wave LDS image; their five late load-wait points per row removed
# baseline (speedup 1.0000x reference)
; __global__ void __launch_bounds__(NWAVES * 64, 2) mk_fwd(Args args) {
;     ...
;                 const float* gq = args.in[23] + (size_t)l * QL; const float* gkv = args.in[24] + (size_t)l * KVL; const float* gkr = args.in[31] + (size_t)l * ROPE;
;                 const float* cw = args.in[32] + (size_t)l * 3 * CONVD; const float* cb = args.in[33] + (size_t)l * CONVD;
;                 for (int m = gw; m < M; m += ngw) {
.LBB0_498:
	v_readlane_b32 s36, v252, 4
	s_lshl_b64 s[2:3], s[48:49], 2
	v_readlane_b32 s42, v252, 10
	v_readlane_b32 s37, v252, 5
	v_readlane_b32 s43, v252, 11
	s_add_u32 s36, s42, s2
	v_readlane_b32 s38, v252, 6
	s_addc_u32 s37, s43, s3
	s_ashr_i32 s2, s10, 6
	s_lshl_b32 s3, s1, 3
	s_add_i32 s38, s3, s2
	s_add_i32 s38, s38, 0x700
	s_and_b32 s38, s38, 0x7ff
	s_lshl_b32 s50, s0, 3
	s_add_u32 s2, s52, 0x4a700000
	s_addc_u32 s3, s53, 0
	v_writelane_b32 v254, s2, 62
	v_and_b32_e32 v108, 63, v109
	v_readlane_b32 s39, v252, 7
	v_writelane_b32 v254, s3, 63
	s_add_u32 s2, s52, 0x4d800000
	s_addc_u32 s3, s53, 0
	v_writelane_b32 v255, s2, 0
	s_cmpk_gt_i32 s38, 0x41ff
	v_readlane_b32 s40, v252, 8
	v_writelane_b32 v255, s3, 1
	v_readlane_b32 s41, v252, 9
	s_waitcnt vmcnt(0) lgkmcnt(0)
	s_barrier
	s_cbranch_scc1 .LBB0_597
; __global__ void __launch_bounds__(NWAVES * 64, 2) mk_fwd(Args args) {
;     ...
;                 const float* gq = args.in[23] + (size_t)l * QL; const float* gkv = args.in[24] + (size_t)l * KVL; const float* gkr = args.in[31] + (size_t)l * ROPE;
;                 const float* cw = args.in[32] + (size_t)l * 3 * CONVD; const float* cb = args.in[33] + (size_t)l * CONVD;
;     ...
;                         for (int j = 0; j < 2; ++j) { const f32x4 g0 = *(const f32x4*)(gq + j * 512 + lane * 8), g1 = *(const f32x4*)(gq + j * 512 + lane * 8 + 4);
;     ...
;                         const f32x4 g0 = *(const f32x4*)(gkv + lane * 8), g1 = *(const f32x4*)(gkv + lane * 8 + 4);
	s_add_u32 s52, s52, 0x100000
	v_readlane_b32 s56, v252, 4
	s_addc_u32 s53, s53, 0
	s_lshl_b64 s[2:3], s[54:55], 2
	v_readlane_b32 s58, v252, 6
	v_readlane_b32 s59, v252, 7
	s_add_u32 s4, s58, s2
	v_readlane_b32 s40, v254, 54
	s_addc_u32 s5, s59, s3
	s_mul_i32 s6, s40, 0x3000
	v_readlane_b32 s57, v252, 5
	v_readlane_b32 s60, v252, 8
	v_readlane_b32 s61, v252, 9
	v_readlane_b32 s62, v252, 10
	v_readlane_b32 s63, v252, 11
	s_add_u32 s6, s56, s6
	v_readlane_b32 s41, v254, 55
	s_addc_u32 s7, s57, 0
	v_readlane_b32 s56, v252, 18
	s_lshl_b64 s[8:9], s[40:41], 8
	v_readlane_b32 s70, v252, 32
	v_readlane_b32 s71, v252, 33
	s_add_u32 s8, s70, s8
	s_addc_u32 s9, s71, s9
	s_lshl_b64 s[54:55], s[40:41], 11
	v_readlane_b32 s57, v252, 19
	v_readlane_b32 s58, v252, 20
	v_readlane_b32 s59, v252, 21
	v_readlane_b32 s60, v252, 22
	v_readlane_b32 s61, v252, 23
	v_readlane_b32 s62, v252, 24
	v_readlane_b32 s63, v252, 25
	v_readlane_b32 s64, v252, 26
	v_readlane_b32 s65, v252, 27
	v_readlane_b32 s66, v252, 28
	v_readlane_b32 s67, v252, 29
	v_readlane_b32 s68, v252, 30
	v_readlane_b32 s69, v252, 31
	s_add_u32 s54, s56, s54
	s_addc_u32 s55, s57, s55
	v_readlane_b32 s56, v252, 52
	v_readlane_b32 s70, v253, 2
	v_readlane_b32 s71, v253, 3
	s_add_u32 s2, s70, s2
	s_addc_u32 s3, s71, s3
	s_add_u32 s19, s36, 0x10800000
	s_addc_u32 s72, s37, 0
	s_lshl_b32 s73, s40, 2
	s_add_u32 s74, s36, 0x15229000
	s_addc_u32 s75, s37, 0
	s_lshl_b32 s76, s40, 4
	s_add_u32 s77, s36, 0x14800000
	s_addc_u32 s78, s37, 0
	s_add_u32 s79, s36, 0x15429000
	v_cmp_lt_i32_e32 vcc, v192, v191
	s_addc_u32 s96, s37, 0
	s_add_u32 s97, s36, 0x15219000
	v_cndmask_b32_e32 v8, v190, v192, vcc
	v_cmp_lt_i32_e32 vcc, v193, v191
	v_xor_b32_e32 v2, 4, v190
	s_addc_u32 s40, s37, 0
	v_cndmask_b32_e32 v9, v190, v193, vcc
	v_cmp_lt_i32_e32 vcc, v202, v191
	s_add_u32 s41, s36, 0x15ccd000
	s_addc_u32 s42, s37, 0
	v_cndmask_b32_e32 v10, v190, v202, vcc
	v_cmp_lt_i32_e32 vcc, v2, v191
	s_ashr_i32 s39, s38, 31
	s_ashr_i32 s51, s50, 31
	v_cndmask_b32_e32 v11, v190, v2, vcc
	v_lshlrev_b32_e32 v2, 5, v108
	v_lshl_add_u64 v[110:111], s[2:3], 0, v[2:3]
	v_lshl_add_u64 v[118:119], s[6:7], 0, v[2:3]
	s_lshl_b64 s[2:3], s[38:39], 11
	v_readlane_b32 s6, v252, 12
	v_readlane_b32 s7, v252, 13
	s_add_u32 s2, s6, s2
	v_lshl_add_u64 v[112:113], s[54:55], 0, v[2:3]
	v_lshlrev_b32_e32 v4, 4, v108
	v_mov_b32_e32 v5, v3
	v_lshl_add_u64 v[116:117], s[4:5], 0, v[2:3]
	s_addc_u32 s3, s7, s3
	s_lshl_b64 s[54:55], s[50:51], 11
	s_mul_i32 s5, s38, 0x5e00
	v_lshl_add_u64 v[120:121], s[2:3], 0, v[4:5]
	s_mul_hi_i32 s4, s38, 0x5e00
	s_add_u32 s2, s6, s5
	s_addc_u32 s3, s7, s4
	v_lshl_add_u64 v[122:123], s[2:3], 0, v[4:5]
	s_lshl_b64 s[2:3], s[38:39], 13
	s_add_u32 s2, s6, s2
	v_readlane_b32 s57, v252, 53
	s_addc_u32 s3, s7, s3
	v_lshl_add_u64 v[124:125], s[2:3], 0, v[4:5]
	s_lshl_b64 s[56:57], s[50:51], 13
	v_readlane_b32 s2, v254, 31
	s_add_u32 s2, s2, s5
	v_readlane_b32 s3, v254, 32
	s_addc_u32 s3, s3, s4
	v_readlane_b32 s4, v254, 62
	v_readlane_b32 s5, v254, 63
	v_cmp_lt_i32_e32 vcc, v196, v191
	v_readlane_b32 s58, v252, 54
	v_lshl_add_u64 v[128:129], s[4:5], 0, v[4:5]
	v_readlane_b32 s4, v255, 0
	v_lshlrev_b32_e32 v4, 1, v108
	v_readlane_b32 s5, v255, 1
	v_cndmask_b32_e32 v12, v190, v196, vcc
	v_cmp_lt_i32_e32 vcc, v197, v191
	v_lshl_add_u64 v[130:131], s[4:5], 0, v[4:5]
	s_mov_b64 s[4:5], 0x1000
	v_lshl_add_u64 v[132:133], v[118:119], 0, s[4:5]
	s_mov_b64 s[4:5], 0x2000
	v_lshl_add_u64 v[134:135], v[118:119], 0, s[4:5]
	s_mov_b64 s[4:5], 0x800
	v_lshl_add_u64 v[136:137], v[118:119], 0, s[4:5]
	s_mov_b64 s[4:5], 0x1800
	v_readlane_b32 s59, v252, 55
	v_readlane_b32 s60, v252, 56
	v_readlane_b32 s61, v252, 57
	v_cndmask_b32_e32 v13, v190, v197, vcc
	v_lshlrev_b32_e32 v6, 2, v108
	v_mov_b32_e32 v7, v3
	v_lshl_add_u64 v[138:139], v[118:119], 0, s[4:5]
	s_mov_b64 s[4:5], 0x2800
	v_lshl_add_u64 v[114:115], s[8:9], 0, v[6:7]
	v_lshlrev_b32_e32 v126, 3, v108
	v_lshlrev_b32_e32 v174, 2, v8
	v_lshlrev_b32_e32 v175, 2, v9
	v_lshlrev_b32_e32 v176, 2, v10
	v_lshlrev_b32_e32 v177, 2, v11
	v_lshlrev_b32_e32 v178, 2, v12
	v_lshlrev_b32_e32 v179, 2, v13
	v_lshl_add_u64 v[140:141], v[118:119], 0, s[4:5]
	v_lshl_add_u64 v[142:143], s[2:3], 0, v[4:5]
	s_mul_hi_i32 s59, s50, 0x5e00
	s_mul_i32 s58, s50, 0x5e00
	v_lshlrev_b32_e32 v180, 2, v108
	v_cmp_gt_u32_e64 s[2:3], 32, v108
	s_mov_b64 s[60:61], s[38:39]
	v_readlane_b32 s62, v252, 58
	v_readlane_b32 s63, v252, 59
	v_readlane_b32 s64, v252, 60
	v_readlane_b32 s65, v252, 61
	v_readlane_b32 s66, v252, 62
	v_readlane_b32 s67, v252, 63
	v_readlane_b32 s68, v253, 0
	v_readlane_b32 s69, v253, 1
	global_load_dwordx4 v[206:209], v[110:111], off offset:2048
	global_load_dwordx4 v[210:213], v[110:111], off offset:2064
	global_load_dwordx4 v[214:217], v[112:113], off
	global_load_dwordx4 v[218:221], v[112:113], off offset:16
	global_load_dwordx4 v[222:225], v[116:117], off offset:16
	global_load_dwordx4 v[226:229], v[116:117], off
	global_load_dwordx4 v[230:233], v[118:119], off offset:16
	global_load_dwordx4 v[234:237], v[118:119], off
	global_load_dwordx4 v[240:243], v[132:133], off offset:16
	global_load_dwordx4 v[244:247], v[132:133], off
	global_load_dwordx4 v[184:187], v[134:135], off offset:16
	global_load_dwordx2 v[194:195], v[134:135], off
	global_load_dwordx2 v[248:249], v[134:135], off offset:8
	global_load_dword v238, v[114:115], off
	global_load_dwordx4 v[40:43], v[116:117], off offset:2064
	global_load_dwordx4 v[60:63], v[116:117], off offset:2048
	global_load_dwordx4 v[48:51], v[136:137], off offset:16
	global_load_dwordx4 v[72:75], v[136:137], off
	global_load_dwordx4 v[52:55], v[138:139], off offset:16
	global_load_dwordx4 v[64:67], v[138:139], off
	global_load_dwordx4 v[56:59], v[140:141], off offset:16
	global_load_dwordx4 v[68:71], v[140:141], off
	v_lshrrev_b32_e32 v181, 6, v0
	v_and_b32_e32 v4, 63, v0
	v_lshlrev_b32_e32 v181, 13, v181
	v_lshl_add_u32 v181, v4, 4, v181
	s_waitcnt vmcnt(0)
	ds_write_b128 v181, v[40:43]
	ds_write_b128 v181, v[60:63] offset:1024
	ds_write_b128 v181, v[48:51] offset:2048
	ds_write_b128 v181, v[72:75] offset:3072
	ds_write_b128 v181, v[52:55] offset:4096
	ds_write_b128 v181, v[64:67] offset:5120
	ds_write_b128 v181, v[56:59] offset:6144
	ds_write_b128 v181, v[68:71] offset:7168
	s_waitcnt lgkmcnt(0)
	s_branch .LBB0_501

; __global__ void __launch_bounds__(NWAVES * 64, 2) mk_fwd(Args args) {
;     ...
;                 for (int m = gw; m < M; m += ngw) {
;                     const bool smp = m >= MP;
;                     const int b = smp ? ((m - MP) >> 5) : (m >> 12), t = smp ? ((m - MP) & 31) : (m & 4095);
;                     const int pos = smp ? PAST + t : t;
;                     const int T = smp ? DS : SEQ;
;                     const size_t lrow = smp ? (size_t)MP + (size_t)b * SKEYS + PAST + t : (size_t)m;
;                     float* lat_out = smp ? out + O_LATS + ((size_t)(l * DB + b) * DS + t) * KVL : out + O_LATP + ((size_t)(l * NB + b) * SEQ + t) * KVL;
;                     float* kr_out = smp ? out + O_KRS + ((size_t)(l * DB + b) * DS + t) * ROPE : out + O_KRP + ((size_t)(l * NB + b) * SEQ + t) * ROPE;
;                     const bf16_t* prow = proj + (size_t)m * NPAD;
;                     const u32x4 rq0 = *(const u32x4*)(prow + C_CQ + lane * 8), rq1 = *(const u32x4*)(prow + C_CQ + 512 + lane * 8), rkv = *(const u32x4*)(prow + C_CKV + lane * 8);
;                     const bf16_t rkr = prow[C_KR + lane];
;                     u32x4 rgt[6];
; #pragma unroll
;                     for (int j = 0; j < 6; ++j) { const int c = j * 512 + lane * 8; rgt[j] = *(const u32x4*)(prow + (c < RW ? C_RWGATE + c : C_MGATE + (c - RW))); }
;                     const bf16_t* prow1 = t >= 1 ? prow - NPAD : prow; const bf16_t* prow2 = t >= 2 ? prow - 2 * NPAD : prow;
;                     u32x4 rcc[2][3], rcx[2][3], rvb[2], rvg[2];
; #pragma unroll
;                     for (int j = 0; j < 2; ++j) { const int c = j * 512 + lane * 8;
;                         rcc[j][0] = *(const u32x4*)(prow + C_CVC + c); rcx[j][0] = *(const u32x4*)(prow + C_CVX + c);
;                         rcc[j][1] = *(const u32x4*)(prow1 + C_CVC + c); rcx[j][1] = *(const u32x4*)(prow1 + C_CVX + c);
;                         rcc[j][2] = *(const u32x4*)(prow2 + C_CVC + c); rcx[j][2] = *(const u32x4*)(prow2 + C_CVX + c);
;                         rvb[j] = *(const u32x4*)(prow + C_CVB + c); rvg[j] = *(const u32x4*)(prow + C_CVG + c); }
;                     const float2 cs = tab[pos * 32 + (lane & 31)];
;                     {
;                         float f[16]; unpack8(rq0, f); unpack8(rq1, f + 8);
;                         float ss = 0.f;
; #pragma unroll
.LBB0_511:
	v_lshl_add_u64 v[32:33], v[122:123], 0, s[48:49]
	v_add_co_u32_e32 v4, vcc, 0x13302000, v32
	s_mov_b32 s43, 0x13304000
	s_nop 0
	v_addc_co_u32_e32 v5, vcc, 0, v33, vcc
	global_load_dwordx4 v[44:47], v[4:5], off offset:256
	global_load_dwordx4 v[48:51], v[4:5], off offset:1280
	global_load_dwordx4 v[96:99], v[110:111], off offset:16
	global_load_dwordx4 v[100:103], v[110:111], off
	v_add_co_u32_e32 v6, vcc, s43, v32
	s_mov_b32 s80, 0x13305000
	s_nop 0
	v_addc_co_u32_e32 v7, vcc, 0, v33, vcc
	s_and_b64 s[62:63], s[8:9], exec
	v_add_co_u32_e32 v34, vcc, s80, v32
	s_cselect_b32 s10, s39, s85
	s_cselect_b32 s39, s66, s67
	v_addc_co_u32_e32 v35, vcc, 0, v33, vcc
	v_add_co_u32_e32 v8, vcc, 0x13301000, v32
	s_cmp_lg_u32 s39, 0
	s_nop 0
	v_addc_co_u32_e32 v9, vcc, 0, v33, vcc
	s_cselect_b64 s[62:63], -1, 0
	s_cmp_eq_u32 s39, 0
	v_add_co_u32_e32 v52, vcc, 0x13303000, v32
	s_cselect_b32 s71, 0, -1
	s_cselect_b32 s70, 0, 0xffffa200
	v_addc_co_u32_e32 v53, vcc, 0, v33, vcc
	v_lshl_add_u64 v[54:55], v[32:33], 0, s[70:71]
	s_cmp_lt_u32 s39, 2
	s_cselect_b64 s[66:67], -1, 0
	s_cmp_gt_u32 s39, 1
	s_cselect_b32 s71, -1, 0
	s_cselect_b32 s70, 0xffff4400, 0
	global_load_dwordx4 v[68:71], v[6:7], off offset:3456
	global_load_dwordx4 v[36:39], v[6:7], off offset:2432
	global_load_dwordx4 v[60:63], v[34:35], off offset:1408
	global_load_dwordx4 v[40:43], v[34:35], off offset:384
	global_load_dwordx4 v[72:75], v[6:7], off offset:1408
	global_load_dwordx4 v[28:31], v[6:7], off offset:384
	global_load_dwordx4 v[92:95], v[4:5], off offset:2304
	global_load_dwordx4 v[16:19], v[4:5], off offset:3456
	global_load_dwordx4 v[24:27], v[8:9], off offset:2304
	global_load_dwordx4 v[20:23], v[8:9], off offset:3328
	global_load_dwordx4 v[12:15], v[52:53], off offset:384
	s_nop 0
	global_load_dwordx4 v[8:11], v[52:53], off offset:1408
	global_load_dwordx4 v[4:7], v[52:53], off offset:2432
	global_load_dwordx4 v[64:67], v[52:53], off offset:3456
	s_lshl_b32 s86, s39, 5
	s_add_i32 s87, s86, 0x10000
	v_lshl_add_u64 v[104:105], v[142:143], 0, s[48:49]
	v_lshl_add_u64 v[106:107], v[120:121], 0, s[48:49]
	s_waitcnt vmcnt(17)
	v_and_b32_e32 v151, 0xffff0000, v44
	v_lshlrev_b32_e32 v150, 16, v44
	v_mul_f32_e32 v2, v151, v151
	v_lshlrev_b32_e32 v152, 16, v45
	v_fmac_f32_e32 v2, v150, v150
	v_and_b32_e32 v153, 0xffff0000, v45
	v_fmac_f32_e32 v2, v152, v152
	v_lshlrev_b32_e32 v154, 16, v46
	v_fmac_f32_e32 v2, v153, v153
	v_and_b32_e32 v155, 0xffff0000, v46
	v_fmac_f32_e32 v2, v154, v154
	v_lshlrev_b32_e32 v156, 16, v47
	v_fmac_f32_e32 v2, v155, v155
	v_and_b32_e32 v157, 0xffff0000, v47
	v_fmac_f32_e32 v2, v156, v156
	s_waitcnt vmcnt(16)
	v_lshlrev_b32_e32 v158, 16, v48
	v_fmac_f32_e32 v2, v157, v157
	v_and_b32_e32 v159, 0xffff0000, v48
	v_fmac_f32_e32 v2, v158, v158
	v_lshlrev_b32_e32 v160, 16, v49
	v_fmac_f32_e32 v2, v159, v159
	v_and_b32_e32 v161, 0xffff0000, v49
	v_lshlrev_b32_e32 v146, 16, v50
	v_and_b32_e32 v147, 0xffff0000, v50
	v_fmac_f32_e32 v2, v160, v160
	v_pk_mul_f32 v[44:45], v[146:147], v[146:147]
	v_fmac_f32_e32 v2, v161, v161
	v_lshlrev_b32_e32 v144, 16, v51
	v_and_b32_e32 v145, 0xffff0000, v51
	v_add_f32_e32 v2, v2, v44
	v_pk_mul_f32 v[46:47], v[144:145], v[144:145]
	v_add_f32_e32 v2, v2, v45
	v_add_f32_e32 v2, v2, v46
	v_add_f32_e32 v2, v2, v47
	ds_bpermute_b32 v46, v174, v2
	v_add_co_u32_e32 v44, vcc, s43, v54
	v_lshl_add_u64 v[48:49], v[32:33], 0, s[70:71]
	s_nop 0
	v_addc_co_u32_e32 v45, vcc, 0, v55, vcc
	s_waitcnt lgkmcnt(0)
	v_add_f32_e32 v2, v2, v46
	ds_bpermute_b32 v50, v175, v2
	v_add_co_u32_e32 v46, vcc, s80, v54
	s_and_b64 s[70:71], s[8:9], exec
	s_nop 0
	v_addc_co_u32_e32 v47, vcc, 0, v55, vcc
	s_waitcnt lgkmcnt(0)
	v_add_f32_e32 v2, v2, v50
	ds_bpermute_b32 v50, v176, v2
	global_load_dwordx4 v[84:87], v[44:45], off offset:1408
	global_load_dwordx4 v[56:59], v[44:45], off offset:2432
	global_load_dwordx4 v[52:55], v[46:47], off offset:384
	s_nop 0
	global_load_dwordx4 v[32:35], v[34:35], off offset:2432
	v_add_co_u32_e32 v46, vcc, s43, v48
	s_cselect_b32 s70, s87, s86
	s_waitcnt lgkmcnt(0)
	v_add_f32_e32 v2, v2, v50
	ds_bpermute_b32 v50, v177, v2
	v_addc_co_u32_e32 v47, vcc, 0, v49, vcc
	v_add_co_u32_e32 v148, vcc, s80, v48
	s_waitcnt lgkmcnt(0)
	v_add_f32_e32 v2, v2, v50
	ds_bpermute_b32 v50, v178, v2
	v_addc_co_u32_e32 v149, vcc, 0, v49, vcc
	global_load_dwordx4 v[88:91], v[44:45], off offset:3456
	global_load_dwordx4 v[80:83], v[46:47], off offset:1408
	s_waitcnt lgkmcnt(0)
	v_add_f32_e32 v2, v2, v50
	ds_bpermute_b32 v162, v179, v2
	global_load_dwordx4 v[76:79], v[46:47], off offset:3456
	global_load_dwordx4 v[48:51], v[46:47], off offset:2432
	s_nop 0
	global_load_dwordx4 v[44:47], v[148:149], off offset:384
	s_waitcnt lgkmcnt(0)
	v_add_f32_e32 v2, v2, v162
	v_fmamk_f32 v2, v2, 0x3a800000, v1
	v_mul_f32_e32 v148, 0x4b800000, v2
	v_cmp_gt_f32_e32 vcc, s33, v2
	s_nop 1
	v_cndmask_b32_e32 v2, v2, v148, vcc
	v_rsq_f32_e32 v162, v2
	v_or_b32_e32 v2, s70, v127
	v_lshl_add_u64 v[148:149], v[2:3], 3, s[52:53]
	s_mov_b32 s70, 0x200000
	v_mul_f32_e32 v2, 0x45800000, v162
	v_cndmask_b32_e32 v2, v162, v2, vcc
	v_mul_f32_e32 v150, v2, v150
	v_mul_f32_e32 v154, v2, v154
	s_waitcnt vmcnt(23)
; __device__ __forceinline__ float bf2f(bf16_t b) { return __uint_as_float((unsigned)b << 16); }
; __device__ __forceinline__ bf16_t f2bf(float f) { return (bf16_t)(cvtpk(f, 0.f) & 0xffffu); }
; __device__ __forceinline__ u32x4 pack8(const float* f) { u32x4 w; w.x = cvtpk(f[0], f[1]); w.y = cvtpk(f[2], f[3]); w.z = cvtpk(f[4], f[5]); w.w = cvtpk(f[6], f[7]); return w; }
; __global__ void __launch_bounds__(NWAVES * 64, 2) mk_fwd(Args args) {
;     ...
;                         const float rstd = rsqrtf(wave_sum(ss) * (1.f / QL) + NORM_EPS);
; #pragma unroll
;                         for (int j = 0; j < 2; ++j) { const f32x4 g0 = *(const f32x4*)(gq + j * 512 + lane * 8), g1 = *(const f32x4*)(gq + j * 512 + lane * 8 + 4);
;                             float y[8];
; #pragma unroll
;                             for (int e = 0; e < 4; ++e) { y[e] = f[j * 8 + e] * rstd * g0[e]; y[4 + e] = f[j * 8 + 4 + e] * rstd * g1[e]; }
;                             *(u32x4*)(qin + (size_t)m * QL + j * 512 + lane * 8) = pack8(y); }
;                     }
;                     {
;                         float f[8]; unpack8(rkv, f);
;                         float ss = 0.f;
; #pragma unroll
;                         for (int e = 0; e < 8; ++e) ss += f[e] * f[e];
;                         const float rstd = rsqrtf(wave_sum(ss) * (1.f / KVL) + NORM_EPS);
;                         const f32x4 g0 = *(const f32x4*)(gkv + lane * 8), g1 = *(const f32x4*)(gkv + lane * 8 + 4);
;                         float y[8];
; #pragma unroll
;                         for (int e = 0; e < 4; ++e) { y[e] = f[e] * rstd * g0[e]; y[4 + e] = f[4 + e] * rstd * g1[e]; }
;                         *(f32x4*)(lat_out + lane * 8) = (f32x4){y[0], y[1], y[2], y[3]}; *(f32x4*)(lat_out + lane * 8 + 4) = (f32x4){y[4], y[5], y[6], y[7]};
;                         *(u32x4*)(latall + lrow * KVL + lane * 8) = pack8(y);
;                     }
;                     {
;                         const float x = bf2f(rkr);
;                         const float rstd = rsqrtf(wave_sum(x * x) * (1.f / ROPE) + NORM_EPS);
;                         const float y = x * rstd * gkr[lane];
;                         const float pt = __shfl_xor(y, 32);
;                         const float o = lane < 32 ? y * cs.x - pt * cs.y : y * cs.x + pt * cs.y;
;                         kr_out[lane] = o; Krb[lrow * ROPE + lane] = f2bf(o);
	v_mul_f32_e32 v100, v100, v150
	v_mul_f32_e32 v150, v96, v154
	v_mul_f32_e32 v96, v2, v151
	v_mul_f32_e32 v96, v101, v96
	v_mul_f32_e32 v101, v2, v155
	v_mul_f32_e32 v101, v97, v101
	v_mul_f32_e32 v97, v2, v152
	v_mul_f32_e32 v97, v102, v97
	v_mul_f32_e32 v102, v2, v156
	v_mul_f32_e32 v102, v98, v102
	v_mul_f32_e32 v98, v2, v153
	v_mul_f32_e32 v98, v103, v98
	v_mul_f32_e32 v103, v2, v157
	global_load_ushort v154, v[104:105], off
	v_add_co_u32_e32 v104, vcc, s70, v106
	v_mul_f32_e32 v99, v99, v103
	s_nop 0
	v_addc_co_u32_e32 v105, vcc, 0, v107, vcc
	global_load_dwordx2 v[148:149], v[148:149], off
	v_cvt_pk_bf16_f32 v96, v100, v96
	v_cvt_pk_bf16_f32 v97, v97, v98
	v_cvt_pk_bf16_f32 v98, v150, v101
	v_cvt_pk_bf16_f32 v99, v102, v99
	global_store_dwordx4 v[104:105], v[96:99], off
	s_nop 1
	v_mov_b64_e32 v[96:97], v[206:207]
	v_mov_b64_e32 v[98:99], v[208:209]
	s_nop 0
	v_mov_b64_e32 v[100:101], v[210:211]
	v_mov_b64_e32 v[102:103], v[212:213]
	v_mul_f32_e32 v106, v2, v158
	v_mul_f32_e32 v107, v2, v146
	v_mul_f32_e32 v146, v2, v159
	v_mul_f32_e32 v150, v2, v160
	v_mul_f32_e32 v151, v2, v161
	v_mul_f32_e32 v147, v2, v147
	v_mul_f32_e32 v144, v2, v144
	v_mul_f32_e32 v2, v2, v145
	s_lshl_b64 s[70:71], s[6:7], 10
	s_lshl_b64 s[6:7], s[6:7], 7
	s_waitcnt vmcnt(1)
	v_mul_f32_e32 v96, v96, v106
	v_mul_f32_e32 v97, v97, v146
	v_mul_f32_e32 v98, v98, v150
	v_mul_f32_e32 v99, v99, v151
	v_mul_f32_e32 v100, v100, v107
	v_mul_f32_e32 v101, v101, v147
	v_mul_f32_e32 v102, v102, v144
	v_mul_f32_e32 v2, v103, v2
	v_cvt_pk_bf16_f32 v96, v96, v97
	v_cvt_pk_bf16_f32 v97, v98, v99
	v_cvt_pk_bf16_f32 v98, v100, v101
	v_cvt_pk_bf16_f32 v99, v102, v2
	global_store_dwordx4 v[104:105], v[96:99], off offset:1024
	s_nop 1
	v_mov_b64_e32 v[96:97], v[214:215]
	v_mov_b64_e32 v[98:99], v[216:217]
	s_nop 0
	v_mov_b64_e32 v[100:101], v[218:219]
	v_mov_b64_e32 v[102:103], v[220:221]
	v_lshlrev_b32_e32 v104, 16, v92
	v_and_b32_e32 v105, 0xffff0000, v92
	v_lshlrev_b32_e32 v92, 16, v93
	v_and_b32_e32 v93, 0xffff0000, v93
	v_pk_mul_f32 v[144:145], v[104:105], v[104:105]
	v_pk_mul_f32 v[146:147], v[92:93], v[92:93]
	v_add_f32_e32 v2, v144, v145
	v_lshlrev_b32_e32 v106, 16, v94
	v_and_b32_e32 v107, 0xffff0000, v94
	v_add_f32_e32 v2, v2, v146
	v_pk_mul_f32 v[150:151], v[106:107], v[106:107]
	v_add_f32_e32 v2, v2, v147
	v_lshlrev_b32_e32 v94, 16, v95
	v_and_b32_e32 v95, 0xffff0000, v95
	v_add_f32_e32 v2, v2, v150
	v_pk_mul_f32 v[152:153], v[94:95], v[94:95]
	v_add_f32_e32 v2, v2, v151
	v_add_f32_e32 v2, v2, v152
	v_add_f32_e32 v2, v2, v153
	ds_bpermute_b32 v144, v174, v2
	v_lshl_add_u64 v[146:147], v[128:129], 0, s[70:71]
	s_mov_b64 s[70:71], -1
	s_waitcnt lgkmcnt(0)
	v_add_f32_e32 v2, v2, v144
	ds_bpermute_b32 v144, v175, v2
	s_waitcnt lgkmcnt(0)
	v_add_f32_e32 v2, v2, v144
	ds_bpermute_b32 v144, v176, v2
	s_waitcnt lgkmcnt(0)
	v_add_f32_e32 v2, v2, v144
	ds_bpermute_b32 v144, v177, v2
	s_waitcnt lgkmcnt(0)
	v_add_f32_e32 v2, v2, v144
	ds_bpermute_b32 v144, v178, v2
	s_waitcnt lgkmcnt(0)
	v_add_f32_e32 v2, v2, v144
	ds_bpermute_b32 v144, v179, v2
	s_waitcnt lgkmcnt(0)
	v_add_f32_e32 v2, v2, v144
	v_fmamk_f32 v2, v2, 0x3b000000, v1
	v_mul_f32_e32 v144, 0x4b800000, v2
	v_cmp_gt_f32_e32 vcc, s33, v2
	s_nop 1
	v_cndmask_b32_e32 v2, v2, v144, vcc
	v_rsq_f32_e32 v2, v2
	v_lshlrev_b32_e32 v144, 2, v126
	v_mul_f32_e32 v145, 0x45800000, v2
	v_cndmask_b32_e32 v2, v2, v145, vcc
	v_pk_mul_f32 v[104:105], v[2:3], v[104:105] op_sel_hi:[0,1]
	v_pk_mul_f32 v[150:151], v[2:3], v[92:93] op_sel_hi:[0,1]
	v_pk_mul_f32 v[106:107], v[2:3], v[106:107] op_sel_hi:[0,1]
	v_pk_mul_f32 v[152:153], v[2:3], v[94:95] op_sel_hi:[0,1]
	v_pk_mul_f32 v[92:93], v[96:97], v[104:105]
	v_pk_mul_f32 v[94:95], v[98:99], v[150:151]
	v_pk_mul_f32 v[96:97], v[100:101], v[106:107]
	v_pk_mul_f32 v[98:99], v[102:103], v[152:153]
	global_store_dwordx4 v144, v[92:95], s[68:69]
	global_store_dwordx4 v144, v[96:99], s[68:69] offset:16
	s_nop 0
	v_cvt_pk_bf16_f32 v92, v92, v93
	v_cvt_pk_bf16_f32 v93, v94, v95
	v_cvt_pk_bf16_f32 v94, v96, v97
	v_cvt_pk_bf16_f32 v95, v98, v99
	global_store_dwordx4 v[146:147], v[92:95], off
	v_mov_b32_e32 v2, v238
	s_nop 0
	v_lshlrev_b32_e32 v92, 16, v154
	v_mul_f32_e32 v93, v92, v92
	ds_bpermute_b32 v93, v174, v93
	s_waitcnt lgkmcnt(0)
	v_fmac_f32_e32 v93, v92, v92
	ds_bpermute_b32 v94, v175, v93
	s_waitcnt lgkmcnt(0)
	v_add_f32_e32 v93, v93, v94
	ds_bpermute_b32 v94, v176, v93
	s_waitcnt lgkmcnt(0)
	v_add_f32_e32 v93, v93, v94
	ds_bpermute_b32 v94, v177, v93
	s_waitcnt lgkmcnt(0)
	v_add_f32_e32 v93, v93, v94
	ds_bpermute_b32 v94, v178, v93
	s_waitcnt lgkmcnt(0)
	v_add_f32_e32 v93, v93, v94
	ds_bpermute_b32 v94, v179, v93
	s_waitcnt lgkmcnt(0)
	v_add_f32_e32 v93, v93, v94
	v_fmamk_f32 v93, v93, 0x3c800000, v1
	v_mul_f32_e32 v94, 0x4b800000, v93
	v_cmp_gt_f32_e32 vcc, s33, v93
	s_nop 1
	v_cndmask_b32_e32 v93, v93, v94, vcc
	v_rsq_f32_e32 v93, v93
	s_nop 0
	v_mul_f32_e32 v94, 0x45800000, v93
	v_cndmask_b32_e32 v93, v93, v94, vcc
	v_mul_f32_e32 v92, v93, v92
	s_and_b64 vcc, exec, s[4:5]
	v_mul_f32_e32 v2, v2, v92
	ds_bpermute_b32 v94, v174, v2
	v_lshl_add_u64 v[92:93], v[130:131], 0, s[6:7]
	s_waitcnt lgkmcnt(0)
	v_mul_f32_e32 v94, v149, v94
	v_cndmask_b32_e64 v94, v94, -v94, s[2:3]
	v_fmac_f32_e32 v94, v148, v2
	global_store_dword v180, v94, s[64:65]
	v_cvt_pk_bf16_f32 v2, v94, v3
	global_store_short v[92:93], v2, off
	s_cbranch_vccz .LBB0_513
	s_add_i32 s4, s85, s73
	s_ashr_i32 s5, s4, 31
	s_lshl_b64 s[4:5], s[4:5], 13
	s_add_u32 s68, s97, s4
	s_addc_u32 s69, s40, s5
	s_mov_b64 s[70:71], 0

; __device__ __forceinline__ float siluf_(float x) { return x * __builtin_amdgcn_rcpf(1.0f + __expf(-x)); }
; __global__ void __launch_bounds__(NWAVES * 64, 2) mk_fwd(Args args) {
;     ...
;                     {
;                         const float* cbuf = args.in[8] + (size_t)(l * DB + b) * 2 * CONVD;
;                         float* cv_out = smp ? out + O_CVS + (size_t)(l * DB + b) * 2 * CONVD : out + O_CVP + (size_t)(l * NB + b) * 2 * CONVD;
; #pragma unroll
;                         for (int j = 0; j < 2; ++j) {
;                             const int c = j * 512 + lane * 8;
;                             float u0[8], u1[8], u2[8], fa[8], fb[8];
;                             unpack8(rcc[j][0], fa); unpack8(rcx[j][0], fb);
; #pragma unroll
;                             for (int e = 0; e < 8; ++e) u0[e] = fa[e] * fb[e];
;                             if (t >= 1) { unpack8(rcc[j][1], fa); unpack8(rcx[j][1], fb);
; #pragma unroll
;                                 for (int e = 0; e < 8; ++e) u1[e] = fa[e] * fb[e]; }
;                             else {
; #pragma unroll
;                                 for (int e = 0; e < 8; ++e) u1[e] = smp ? cbuf[CONVD + c + e] : 0.f; }
;                             if (t >= 2) { unpack8(rcc[j][2], fa); unpack8(rcx[j][2], fb);
; #pragma unroll
;                                 for (int e = 0; e < 8; ++e) u2[e] = fa[e] * fb[e]; }
;                             else {
; #pragma unroll
;                                 for (int e = 0; e < 8; ++e) u2[e] = smp ? cbuf[t * CONVD + c + e] : 0.f; }
;                             float vb[8], vg[8], y[8];
;                             unpack8(rvb[j], vb); unpack8(rvg[j], vg);
; #pragma unroll
;                             for (int e = 0; e < 8; ++e) { const float yy = cb[c + e] + u2[e] * cw[c + e] + u1[e] * cw[CONVD + c + e] + u0[e] * cw[2 * CONVD + c + e];
;                                 y[e] = vb[e] * yy * siluf_(vg[e]); }
;                             *(u32x4*)(hmix + (size_t)m * DM + 3072 + c) = pack8(y);
;                             if (t >= T - 2) { float* co = cv_out + (size_t)(t - (T - 2)) * CONVD + c;
;                                 *(f32x4*)co = (f32x4){u0[0], u0[1], u0[2], u0[3]}; *(f32x4*)(co + 4) = (f32x4){u0[4], u0[5], u0[6], u0[7]}; }
;                         }
.LBB0_554:
	s_and_b64 s[6:7], s[8:9], exec
	s_cselect_b32 s6, 30, 0xffe
	v_mov_b32_e32 v2, s6
	v_sub_co_u32_e64 v2, s[6:7], s39, v2
	v_lshlrev_b32_e32 v2, 10, v2
	v_lshlrev_b64 v[76:77], 2, v[2:3]
	v_lshl_add_u64 v[146:147], s[68:69], 0, v[76:77]
	v_lshlrev_b32_e32 v76, 16, v72
	v_and_b32_e32 v77, 0xffff0000, v72
	v_lshlrev_b32_e32 v78, 16, v68
	v_and_b32_e32 v79, 0xffff0000, v68
	v_lshlrev_b32_e32 v72, 16, v73
	v_and_b32_e32 v73, 0xffff0000, v73
	v_lshlrev_b32_e32 v68, 16, v69
	v_and_b32_e32 v69, 0xffff0000, v69
	v_pk_mul_f32 v[76:77], v[76:77], v[78:79]
	v_pk_mul_f32 v[78:79], v[72:73], v[68:69]
	v_lshlrev_b32_e32 v68, 16, v74
	v_and_b32_e32 v69, 0xffff0000, v74
	v_lshlrev_b32_e32 v72, 16, v70
	v_and_b32_e32 v73, 0xffff0000, v70
	v_pk_mul_f32 v[68:69], v[68:69], v[72:73]
	v_lshlrev_b32_e32 v72, 16, v75
	v_and_b32_e32 v73, 0xffff0000, v75
	v_lshlrev_b32_e32 v70, 16, v71
	v_and_b32_e32 v71, 0xffff0000, v71
	v_pk_mul_f32 v[70:71], v[72:73], v[70:71]
	v_mov_b64_e32 v[72:73], v[222:223]
	v_mov_b64_e32 v[74:75], v[224:225]
	v_mov_b64_e32 v[92:93], v[226:227]
	v_mov_b64_e32 v[94:95], v[228:229]
	v_mov_b64_e32 v[80:81], v[230:231]
	v_mov_b64_e32 v[82:83], v[232:233]
	v_mov_b64_e32 v[104:105], v[234:235]
	v_mov_b64_e32 v[106:107], v[236:237]
	v_mov_b64_e32 v[84:85], v[240:241]
	v_mov_b64_e32 v[86:87], v[242:243]
	v_mov_b64_e32 v[96:97], v[244:245]
	v_mov_b64_e32 v[98:99], v[246:247]
	v_mov_b64_e32 v[88:89], v[184:185]
	v_mov_b64_e32 v[90:91], v[186:187]
	v_mov_b64_e32 v[100:101], v[194:195]
	v_mov_b64_e32 v[102:103], v[248:249]
	s_waitcnt vmcnt(0)
	v_mov_b32_e32 v164, v160
	v_mov_b32_e32 v165, v76
	v_mov_b32_e32 v151, v70
	v_mov_b32_e32 v149, v71
	s_waitcnt vmcnt(2)
	v_mov_b32_e32 v182, v96
	v_fma_f32 v2, v172, v104, v92
	s_waitcnt vmcnt(0)
	v_mov_b32_e32 v183, v100
	v_mov_b32_e32 v100, v97
	v_and_b32_e32 v97, 0xffff0000, v60
	v_pk_mul_f32 v[164:165], v[164:165], v[182:183]
	v_lshlrev_b32_e32 v183, 16, v60
	v_mul_f32_e32 v60, 0xbfb8aa3b, v97
	v_exp_f32_e32 v60, v60
	v_fma_f32 v96, v173, v105, v93
	v_mov_b32_e32 v92, v161
	v_mov_b32_e32 v93, v77
	v_pk_mul_f32 v[92:93], v[92:93], v[100:101]
	v_add_f32_e32 v60, 1.0, v60
	v_add_f32_e32 v92, v96, v92
	v_add_f32_e32 v92, v92, v93
	v_rcp_f32_e32 v93, v60
	v_and_b32_e32 v96, 0xffff0000, v64
	v_lshlrev_b32_e32 v182, 16, v64
	v_fma_f32 v60, v162, v106, v94
	v_pk_mul_f32 v[92:93], v[92:93], v[96:97]
	v_mov_b32_e32 v96, v98
	v_mul_f32_e32 v64, v92, v93
	v_mov_b32_e32 v92, v158
	v_mov_b32_e32 v93, v78
	v_mov_b32_e32 v97, v102
	v_pk_mul_f32 v[92:93], v[92:93], v[96:97]
	v_lshlrev_b32_e32 v97, 16, v61
	v_add_f32_e32 v60, v60, v92
	v_add_f32_e32 v92, v60, v93
	v_mul_f32_e32 v60, 0xbfb8aa3b, v97
	v_exp_f32_e32 v60, v60
	v_lshlrev_b32_e32 v96, 16, v65
	v_mov_b32_e32 v102, v99
	v_fmac_f32_e32 v95, v163, v107
	v_add_f32_e32 v60, 1.0, v60
	v_rcp_f32_e32 v93, v60
	v_and_b32_e32 v94, 0xffff0000, v65
	v_fma_f32 v72, v156, v80, v72
	v_fmac_f32_e32 v75, v155, v83
	v_pk_mul_f32 v[92:93], v[92:93], v[96:97]
	v_mov_b32_e32 v96, v159
	v_mov_b32_e32 v97, v79
	v_pk_mul_f32 v[96:97], v[96:97], v[102:103]
	v_add_f32_e32 v2, v2, v164
	v_add_f32_e32 v60, v95, v96
	v_and_b32_e32 v95, 0xffff0000, v61
	v_mul_f32_e32 v61, 0xbfb8aa3b, v95
	v_exp_f32_e32 v61, v61
	v_add_f32_e32 v60, v60, v97
	v_add_f32_e32 v164, v2, v165
	v_mul_f32_e32 v2, 0xbfb8aa3b, v183
	v_add_f32_e32 v61, 1.0, v61
	v_rcp_f32_e32 v61, v61
	v_exp_f32_e32 v2, v2
	v_mul_f32_e32 v92, v92, v93
	v_pk_mul_f32 v[60:61], v[60:61], v[94:95]
	s_nop 0
	v_mul_f32_e32 v65, v60, v61
	v_mov_b32_e32 v60, v152
	v_mov_b32_e32 v61, v68
	v_mov_b32_e32 v94, v84
	v_mov_b32_e32 v95, v88
	v_pk_mul_f32 v[60:61], v[60:61], v[94:95]
	v_lshlrev_b32_e32 v95, 16, v62
	v_add_f32_e32 v60, v72, v60
	v_add_f32_e32 v60, v60, v61
	v_mul_f32_e32 v61, 0xbfb8aa3b, v95
	v_exp_f32_e32 v61, v61
	v_lshlrev_b32_e32 v94, 16, v66
	v_mov_b32_e32 v88, v85
	v_fma_f32 v72, v157, v81, v73
	v_add_f32_e32 v61, 1.0, v61
	v_rcp_f32_e32 v61, v61
	v_and_b32_e32 v73, 0xffff0000, v62
	v_fma_f32 v62, v154, v82, v74
	v_add_f32_e32 v2, 1.0, v2
	v_pk_mul_f32 v[60:61], v[60:61], v[94:95]
	v_rcp_f32_e32 v165, v2
	v_mul_f32_e32 v80, v60, v61
	v_mov_b32_e32 v60, v153
	v_mov_b32_e32 v61, v69
	v_pk_mul_f32 v[60:61], v[60:61], v[88:89]
	v_pk_mul_f32 v[164:165], v[164:165], v[182:183]
	v_add_f32_e32 v60, v72, v60
	v_add_f32_e32 v60, v60, v61
	v_mul_f32_e32 v61, 0xbfb8aa3b, v73
	v_exp_f32_e32 v61, v61
	v_and_b32_e32 v72, 0xffff0000, v66
	v_mul_f32_e32 v2, v164, v165
	v_add_f32_e32 v61, 1.0, v61
	v_rcp_f32_e32 v61, v61
	s_nop 0
	v_pk_mul_f32 v[60:61], v[60:61], v[72:73]
	s_nop 0
	v_mul_f32_e32 v66, v60, v61
	v_mov_b32_e32 v60, v86
	v_mov_b32_e32 v61, v90
	v_pk_mul_f32 v[60:61], v[150:151], v[60:61]
	v_lshlrev_b32_e32 v73, 16, v63
	v_add_f32_e32 v60, v62, v60
	v_add_f32_e32 v60, v60, v61
	v_mul_f32_e32 v61, 0xbfb8aa3b, v73
	v_exp_f32_e32 v61, v61
	v_lshlrev_b32_e32 v72, 16, v67
	v_mov_b32_e32 v90, v87
	v_and_b32_e32 v63, 0xffff0000, v63
	v_add_f32_e32 v61, 1.0, v61
	v_rcp_f32_e32 v61, v61
	v_and_b32_e32 v62, 0xffff0000, v67
	v_pk_mul_f32 v[60:61], v[60:61], v[72:73]
	s_nop 0
	v_mul_f32_e32 v72, v60, v61
	v_pk_mul_f32 v[60:61], v[148:149], v[90:91]
	s_nop 0
	v_add_f32_e32 v60, v75, v60
	v_add_f32_e32 v60, v60, v61
	v_mul_f32_e32 v61, 0xbfb8aa3b, v63
	v_exp_f32_e32 v61, v61
	s_nop 0
	v_add_f32_e32 v61, 1.0, v61
	v_rcp_f32_e32 v61, v61
	s_nop 0
	v_pk_mul_f32 v[60:61], v[60:61], v[62:63]
	s_nop 0
	v_mul_f32_e32 v63, v60, v61
	v_cvt_pk_bf16_f32 v60, v2, v64
	v_cvt_pk_bf16_f32 v61, v92, v65
	v_cvt_pk_bf16_f32 v62, v80, v66
	v_lshl_add_u64 v[80:81], v[124:125], 0, s[48:49]
	v_add_co_u32_e32 v64, vcc, 0xaf01000, v80
	v_cvt_pk_bf16_f32 v63, v72, v63
	s_nop 1
	v_addc_co_u32_e32 v65, vcc, 0, v81, vcc
	s_and_b64 vcc, exec, s[6:7]
	global_store_dwordx4 v[64:65], v[60:63], off offset:2048
	s_cbranch_vccnz .LBB0_556
	v_readfirstlane_b32 s66, v146
	v_readfirstlane_b32 s67, v147
	s_nop 4
	global_store_dwordx4 v144, v[76:79], s[66:67]
	global_store_dwordx4 v144, v[68:71], s[66:67] offset:16

; __device__ __forceinline__ float siluf_(float x) { return x * __builtin_amdgcn_rcpf(1.0f + __expf(-x)); }
; __device__ __forceinline__ u32x4 pack8(const float* f) { u32x4 w; w.x = cvtpk(f[0], f[1]); w.y = cvtpk(f[2], f[3]); w.z = cvtpk(f[4], f[5]); w.w = cvtpk(f[6], f[7]); return w; }
; __device__ __forceinline__ bf16x8 pack8(const f32x4& a, const f32x4& b) { u32x4 w; w.x = cpk(a.x, a.y); w.y = cpk(a.z, a.w); w.z = cpk(b.x, b.y); w.w = cpk(b.z, b.w); return __builtin_bit_cast(bf16x8, w); }
; __global__ void __launch_bounds__(NWAVES * 64, 2) mk_fwd(Args args) {
;     ...
;                         for (int j = 0; j < 2; ++j) {
;                             const int c = j * 512 + lane * 8;
;                             float u0[8], u1[8], u2[8], fa[8], fb[8];
;                             unpack8(rcc[j][0], fa); unpack8(rcx[j][0], fb);
; #pragma unroll
;                             for (int e = 0; e < 8; ++e) u0[e] = fa[e] * fb[e];
;                             if (t >= 1) { unpack8(rcc[j][1], fa); unpack8(rcx[j][1], fb);
; #pragma unroll
;                                 for (int e = 0; e < 8; ++e) u1[e] = fa[e] * fb[e]; }
;                             else {
; #pragma unroll
;                                 for (int e = 0; e < 8; ++e) u1[e] = smp ? cbuf[CONVD + c + e] : 0.f; }
;                             if (t >= 2) { unpack8(rcc[j][2], fa); unpack8(rcx[j][2], fb);
; #pragma unroll
;                                 for (int e = 0; e < 8; ++e) u2[e] = fa[e] * fb[e]; }
;                             else {
; #pragma unroll
;                                 for (int e = 0; e < 8; ++e) u2[e] = smp ? cbuf[t * CONVD + c + e] : 0.f; }
;                             float vb[8], vg[8], y[8];
;                             unpack8(rvb[j], vb); unpack8(rvg[j], vg);
; #pragma unroll
;                             for (int e = 0; e < 8; ++e) { const float yy = cb[c + e] + u2[e] * cw[c + e] + u1[e] * cw[CONVD + c + e] + u0[e] * cw[2 * CONVD + c + e];
;                                 y[e] = vb[e] * yy * siluf_(vg[e]); }
;                             *(u32x4*)(hmix + (size_t)m * DM + 3072 + c) = pack8(y);
;                             if (t >= T - 2) { float* co = cv_out + (size_t)(t - (T - 2)) * CONVD + c;
;                                 *(f32x4*)co = (f32x4){u0[0], u0[1], u0[2], u0[3]}; *(f32x4*)(co + 4) = (f32x4){u0[4], u0[5], u0[6], u0[7]}; }
;                         }
.LBB0_595:
	v_lshlrev_b32_e32 v44, 16, v36
	v_and_b32_e32 v45, 0xffff0000, v36
	v_lshlrev_b32_e32 v46, 16, v40
	v_and_b32_e32 v47, 0xffff0000, v40
	v_lshlrev_b32_e32 v36, 16, v37
	v_and_b32_e32 v37, 0xffff0000, v37
	v_lshlrev_b32_e32 v40, 16, v41
	v_and_b32_e32 v41, 0xffff0000, v41
	v_pk_mul_f32 v[44:45], v[44:45], v[46:47]
	v_pk_mul_f32 v[46:47], v[36:37], v[40:41]
	v_lshlrev_b32_e32 v36, 16, v38
	v_and_b32_e32 v37, 0xffff0000, v38
	v_lshlrev_b32_e32 v40, 16, v42
	v_and_b32_e32 v41, 0xffff0000, v42
	v_pk_mul_f32 v[36:37], v[36:37], v[40:41]
	v_lshlrev_b32_e32 v38, 16, v39
	v_and_b32_e32 v39, 0xffff0000, v39
	v_lshlrev_b32_e32 v40, 16, v43
	v_and_b32_e32 v41, 0xffff0000, v43
	v_pk_mul_f32 v[38:39], v[38:39], v[40:41]
	ds_read_b128 v[40:43], v181
	ds_read_b128 v[60:63], v181 offset:1024
	ds_read_b128 v[48:51], v181 offset:2048
	ds_read_b128 v[72:75], v181 offset:3072
	ds_read_b128 v[52:55], v181 offset:4096
	ds_read_b128 v[64:67], v181 offset:5120
	ds_read_b128 v[56:59], v181 offset:6144
	ds_read_b128 v[68:71], v181 offset:7168
	s_waitcnt vmcnt(0) lgkmcnt(0)
	v_mov_b32_e32 v96, v90
	v_mov_b32_e32 v97, v44
	v_mov_b32_e32 v79, v38
	v_mov_b32_e32 v77, v39
	s_waitcnt vmcnt(2)
	v_mov_b32_e32 v98, v64
	v_fma_f32 v2, v94, v72, v60
	s_waitcnt vmcnt(0)
	v_mov_b32_e32 v99, v68
	v_fma_f32 v64, v95, v73, v61
	v_mov_b32_e32 v60, v91
	v_mov_b32_e32 v61, v45
	v_mov_b32_e32 v68, v65
	v_pk_mul_f32 v[60:61], v[60:61], v[68:69]
	v_and_b32_e32 v65, 0xffff0000, v32
	v_pk_mul_f32 v[96:97], v[96:97], v[98:99]
	v_lshlrev_b32_e32 v98, 16, v28
	v_add_f32_e32 v60, v64, v60
	v_and_b32_e32 v64, 0xffff0000, v28
	v_mul_f32_e32 v28, 0xbfb8aa3b, v65
	v_exp_f32_e32 v28, v28
	v_add_f32_e32 v60, v60, v61
	v_lshlrev_b32_e32 v99, 16, v32
	v_fma_f32 v32, v92, v74, v62
	v_add_f32_e32 v28, 1.0, v28
	v_rcp_f32_e32 v61, v28
	v_fmac_f32_e32 v63, v93, v75
	v_and_b32_e32 v62, 0xffff0000, v29
	v_add_f32_e32 v2, v2, v96
	v_pk_mul_f32 v[60:61], v[60:61], v[64:65]
	v_mov_b32_e32 v64, v66
	v_mul_f32_e32 v28, v60, v61
	v_mov_b32_e32 v60, v88
	v_mov_b32_e32 v61, v46
	v_mov_b32_e32 v65, v70
	v_pk_mul_f32 v[60:61], v[60:61], v[64:65]
	v_lshlrev_b32_e32 v65, 16, v33
	v_add_f32_e32 v32, v32, v60
	v_add_f32_e32 v60, v32, v61
	v_mul_f32_e32 v32, 0xbfb8aa3b, v65
	v_exp_f32_e32 v32, v32
	v_lshlrev_b32_e32 v64, 16, v29
	v_mov_b32_e32 v70, v67
	v_add_f32_e32 v96, v2, v97
	v_add_f32_e32 v32, 1.0, v32
	v_rcp_f32_e32 v61, v32
	v_mul_f32_e32 v2, 0xbfb8aa3b, v99
	v_exp_f32_e32 v2, v2
	v_fmac_f32_e32 v43, v85, v51
	v_pk_mul_f32 v[60:61], v[60:61], v[64:65]
	v_add_f32_e32 v2, 1.0, v2
	v_mul_f32_e32 v32, v60, v61
	v_mov_b32_e32 v60, v89
	v_mov_b32_e32 v61, v47
	v_pk_mul_f32 v[60:61], v[60:61], v[70:71]
	v_rcp_f32_e32 v97, v2
	v_add_f32_e32 v60, v63, v60
	v_and_b32_e32 v63, 0xffff0000, v33
	v_mul_f32_e32 v29, 0xbfb8aa3b, v63
	v_exp_f32_e32 v29, v29
	v_add_f32_e32 v60, v60, v61
	v_fma_f32 v33, v86, v48, v40
	v_fma_f32 v48, v87, v49, v41
	v_add_f32_e32 v29, 1.0, v29
	v_rcp_f32_e32 v61, v29
	v_mov_b32_e32 v40, v83
	v_mov_b32_e32 v41, v37
	v_and_b32_e32 v49, 0xffff0000, v34
	v_pk_mul_f32 v[60:61], v[60:61], v[62:63]
	v_mov_b32_e32 v63, v56
	v_mov_b32_e32 v56, v53
	v_mul_f32_e32 v29, v60, v61
	v_mov_b32_e32 v60, v82
	v_mov_b32_e32 v61, v36
	v_mov_b32_e32 v62, v52
	v_pk_mul_f32 v[40:41], v[40:41], v[56:57]
	v_pk_mul_f32 v[60:61], v[60:61], v[62:63]
	v_lshlrev_b32_e32 v62, 16, v30
	v_add_f32_e32 v40, v48, v40
	v_and_b32_e32 v48, 0xffff0000, v30
	v_mul_f32_e32 v30, 0xbfb8aa3b, v49
	v_exp_f32_e32 v30, v30
	v_add_f32_e32 v40, v40, v41
	v_add_f32_e32 v33, v33, v60
	v_lshlrev_b32_e32 v63, 16, v34
	v_add_f32_e32 v30, 1.0, v30
	v_rcp_f32_e32 v41, v30
	v_fma_f32 v30, v84, v50, v42
	v_add_f32_e32 v60, v33, v61
	v_mul_f32_e32 v33, 0xbfb8aa3b, v63
	v_pk_mul_f32 v[40:41], v[40:41], v[48:49]
	v_lshlrev_b32_e32 v49, 16, v35
	v_mul_f32_e32 v52, v40, v41
	v_mov_b32_e32 v40, v54
	v_mov_b32_e32 v41, v58
	v_pk_mul_f32 v[40:41], v[78:79], v[40:41]
	v_and_b32_e32 v35, 0xffff0000, v35
	v_add_f32_e32 v30, v30, v40
	v_add_f32_e32 v40, v30, v41
	v_mul_f32_e32 v30, 0xbfb8aa3b, v49
	v_exp_f32_e32 v30, v30
	v_exp_f32_e32 v33, v33
	v_lshlrev_b32_e32 v48, 16, v31
	v_and_b32_e32 v34, 0xffff0000, v31
	v_mul_f32_e32 v31, 0xbfb8aa3b, v35
	v_add_f32_e32 v30, 1.0, v30
	v_exp_f32_e32 v31, v31
	v_rcp_f32_e32 v41, v30
	v_add_f32_e32 v33, 1.0, v33
	v_rcp_f32_e32 v61, v33
	v_add_f32_e32 v31, 1.0, v31
	v_pk_mul_f32 v[40:41], v[40:41], v[48:49]
	v_mov_b32_e32 v58, v55
	v_rcp_f32_e32 v31, v31
	v_mul_f32_e32 v42, v40, v41
	v_pk_mul_f32 v[40:41], v[76:77], v[58:59]
	v_pk_mul_f32 v[96:97], v[96:97], v[98:99]
	v_add_f32_e32 v30, v43, v40
	v_pk_mul_f32 v[60:61], v[60:61], v[62:63]
	v_add_f32_e32 v30, v30, v41
	v_mul_f32_e32 v2, v96, v97
	v_mul_f32_e32 v33, v60, v61
	v_pk_mul_f32 v[30:31], v[30:31], v[34:35]
	v_cvt_pk_bf16_f32 v28, v2, v28
	v_cvt_pk_bf16_f32 v29, v32, v29
	v_add_co_u32_e32 v32, vcc, 0xaf01000, v80
	v_mul_f32_e32 v31, v30, v31
	v_cvt_pk_bf16_f32 v30, v33, v52
	s_nop 0
	v_addc_co_u32_e32 v33, vcc, 0, v81, vcc
	s_andn2_b64 vcc, exec, s[6:7]
	v_cvt_pk_bf16_f32 v31, v42, v31
	global_store_dwordx4 v[32:33], v[28:31], off offset:3072
	s_cbranch_vccnz .LBB0_500
	v_readfirstlane_b32 s4, v146
	v_readfirstlane_b32 s5, v147
	s_nop 4
	global_store_dwordx4 v144, v[44:47], s[4:5] offset:2048
	global_store_dwordx4 v144, v[36:39], s[4:5] offset:2064
	s_branch .LBB0_500
